# lever 4: static s_setprio 1 for waves 4-7 during the whole LRU phase (de-phases the two lock-step waves of each SIMD)
# speedup vs baseline: 1.0016x; 1.0016x over previous
; DI LruPar lru_params(const Params& p, int nb) {
;     const int chg = nb * 128 + (int)(threadIdx.x >> 6) * 16 + (int)(threadIdx.x & 15); LruPar r;
; #pragma unroll
;     for (int d = 0; d < 2; ++d) { const float br = p.in[6][d * 2048 + chg], bi = p.in[8][d * 2048 + chg], lam = p.in[9][d * 2048 + chg];
;         r.nbr[d] = -br * LOG2E; r.nbi[d] = -bi * LOG2E; r.cdec[d] = -8.f * log1pf(expf(-lam)) * LOG2E; }
;     return r;
; DI void phase_lru(const Params& p, unsigned char* shm) {
;     int nbp = -1; LruPar par;
;     for (int it = blockIdx.x; it < 2048; it += gridDim.x) { const int nb = it & 15; if (nb != nbp) { par = lru_params(p, nb); nbp = nb; } lru_tile(p, shm, it >> 4, nb, par); }
.LBB0_207:
	s_waitcnt lgkmcnt(0)
	s_cmp_lt_i32 s4, 3
	s_cselect_b64 s[6:7], -1, 0
	s_cmp_gt_i32 s5, 2
	s_cselect_b64 s[4:5], -1, 0
	s_and_b64 s[4:5], s[6:7], s[4:5]
	s_andn2_b64 vcc, exec, s[4:5]
	s_cbranch_vccnz .LBB0_266
	s_load_dword s4, s[0:1], 0xd0
	s_waitcnt lgkmcnt(0)
	s_bitcmp0_b32 s4, 0
	s_cbranch_scc1 .LBB0_234
	s_cmpk_gt_i32 s2, 0x7ff
	s_cbranch_scc1 .LBB0_233
	s_load_dwordx4 s[12:15], s[0:1], 0x40
	s_load_dwordx4 s[16:19], s[0:1], 0x78
	s_load_dwordx4 s[20:23], s[0:1], 0x18
	s_load_dwordx2 s[30:31], s[0:1], 0x30
	s_waitcnt vmcnt(0)
	v_lshrrev_b32_e32 v0, 2, v202
	v_and_b32_e32 v1, 15, v202
	s_movk_i32 s4, 0xf0
	s_waitcnt lgkmcnt(0)
	s_add_u32 s37, s18, 0x1ba00000
	s_addc_u32 s41, s19, 0
	s_add_u32 s34, s18, 0x1c000000
	s_addc_u32 s35, s19, 0
	s_add_u32 s43, s16, 0x4000000
	v_mov_b32_e32 v69, 0
	v_and_or_b32 v71, v0, s4, v1
	s_addc_u32 s45, s17, 0
	s_mov_b32 s70, -1
	s_mov_b32 s36, 0xbfb8aa3b
	s_mov_b32 s47, 0x42ce8ed0
	s_mov_b32 s39, 0
	s_mov_b32 s49, 0xc2b17218
	s_mov_b32 s51, 0x7f800000
	s_movk_i32 s62, 0x2000
	s_mov_b32 s63, 0x3f2aaaab
	s_mov_b32 s40, 0x3e9b6dac
	s_mov_b32 s42, 0x3f2aaada
	s_mov_b32 s44, 0x3f317218
	s_mov_b32 s46, 0xb102e308
	s_mov_b32 s64, 0x33800000
	s_mov_b32 s48, 0xc1000000
	s_mov_b32 s50, 0x3fb8aa3b
	s_mov_b64 s[52:53], 0x2000
	s_mov_b64 s[54:55], 0x4000
	s_movk_i32 s65, 0x4000
	s_mov_b64 s[56:57], 0x6000
	s_movk_i32 s66, 0x6000
	s_movk_i32 s67, 0x110
	s_add_i32 s68, 0, 0x11000
	v_mov_b32_e32 v73, 0x7f800000
	v_mov_b32_e32 v70, 0x3ecc95a3
	s_mov_b32 s69, s2
	v_mov_b32_e32 v180, 0
	v_mov_b32_e32 v162, 0
	v_mov_b32_e32 v91, 0
	v_mov_b32_e32 v89, 0
	v_mov_b32_e32 v85, 0
	v_mov_b32_e32 v81, 0
	v_mov_b32_e32 v79, 0
	v_mov_b32_e32 v77, 0
	v_mov_b32_e32 v90, v69
	v_mov_b32_e32 v88, v69
	v_mov_b32_e32 v84, v69
	v_mov_b32_e32 v80, v69
	v_mov_b32_e32 v78, v69
	v_mov_b32_e32 v76, v69
	v_mov_b32_e32 v74, v69
	v_mov_b32_e32 v72, v69
	v_readfirstlane_b32 s90, v202
	s_cmp_ge_u32 s90, 0x100
	s_cbranch_scc0 .Lprio_lru
	s_setprio 1
.Lprio_lru:
	s_mov_b32 s71, 0
	s_branch .LBB0_212

; DI void phase_lru(const Params& p, unsigned char* shm) {
;     ...
;     __syncthreads();
.LBB0_233:
	s_setprio 0
	s_waitcnt vmcnt(0) lgkmcnt(0)
	s_barrier
